# v10 + nt on the P0 f32 weight loads as well (16 global_load_dwordx4)
# speedup vs baseline: 1.0072x; 1.0010x over previous
.Lp0_segok_l1:
	s_sub_u32 s26, s25, s7
	s_mul_hi_u32 s27, s26, s20
	s_mul_i32 s28, s27, s19
	s_sub_u32 s28, s26, s28
	s_lshl_b32 s29, s28, 5
	s_lshl_b32 s30, s27, 6
	s_mul_i32 s31, s30, s18
	s_lshl_b32 s34, s29, 2
	s_add_u32 s31, s31, s34
	s_add_u32 s56, s14, s31
	s_addc_u32 s57, s15, 0
	s_add_u32 s58, s56, s18
	s_addc_u32 s59, s57, 0
	s_add_u32 s60, s58, s18
	s_addc_u32 s61, s59, 0
	s_add_u32 s62, s60, s18
	s_addc_u32 s63, s61, 0
	s_add_u32 s64, s62, s18
	s_addc_u32 s65, s63, 0
	s_add_u32 s66, s64, s18
	s_addc_u32 s67, s65, 0
	s_add_u32 s68, s66, s18
	s_addc_u32 s69, s67, 0
	s_add_u32 s70, s68, s18
	s_addc_u32 s71, s69, 0
	s_lshl_b32 s34, s30, 2
	s_add_u32 s72, s16, s34
	s_addc_u32 s73, s17, 0
	s_cmpk_ge_u32 s29, 0x1600
	s_cselect_b32 s34, 1, 0
	s_and_b32 s34, s34, s24
	s_mul_i32 s35, s34, 0x1600
	s_sub_u32 s35, s29, s35
	s_lshr_b32 s36, s35, 7
	s_lshl_b32 s36, s36, 8
	s_lshl_b32 s37, s34, 7
	s_add_u32 s36, s36, s37
	s_and_b32 s37, s35, 0x7f
	s_add_u32 s36, s36, s37
	s_cmp_eq_u32 s24, 0
	s_cselect_b32 s36, s29, s36
	s_lshr_b32 s37, s36, 8
	s_mul_i32 s37, s37, s21
	s_add_u32 s37, s37, s27
	s_lshl_b32 s37, s37, 8
	s_and_b32 s38, s36, 0xff
	s_add_u32 s37, s37, s38
	s_lshl_b32 s37, s37, 7
	s_add_u32 s54, s22, s37
	s_addc_u32 s55, s23, 0
	s_mov_b32 s49, s13
	v_mad_u32_u24 v10, v2, s18, v1
	global_load_dwordx4 v[68:71], v3, s[72:73]
	global_load_dwordx4 v[72:75], v3, s[72:73] offset:16
	global_load_dwordx4 v[76:79], v10, s[56:57] nt
	global_load_dwordx4 v[80:83], v10, s[58:59] nt
	global_load_dwordx4 v[84:87], v10, s[60:61] nt
	global_load_dwordx4 v[88:91], v10, s[62:63] nt
	global_load_dwordx4 v[92:95], v10, s[64:65] nt
	global_load_dwordx4 v[96:99], v10, s[66:67] nt
	global_load_dwordx4 v[100:103], v10, s[68:69] nt
	global_load_dwordx4 v[104:107], v10, s[70:71] nt
	s_waitcnt vmcnt(14)
	s_cmp_eq_u32 s48, 0
	s_cbranch_scc1 .Lp0_nomul_pa
	v_mul_f32_e32 v36, v36, v28
	v_mul_f32_e32 v37, v37, v28
	v_mul_f32_e32 v38, v38, v28
	v_mul_f32_e32 v39, v39, v28
	v_mul_f32_e32 v40, v40, v29
	v_mul_f32_e32 v41, v41, v29
	v_mul_f32_e32 v42, v42, v29
	v_mul_f32_e32 v43, v43, v29
	v_mul_f32_e32 v44, v44, v30
	v_mul_f32_e32 v45, v45, v30
	v_mul_f32_e32 v46, v46, v30
	v_mul_f32_e32 v47, v47, v30
	v_mul_f32_e32 v48, v48, v31
	v_mul_f32_e32 v49, v49, v31
	v_mul_f32_e32 v50, v50, v31
	v_mul_f32_e32 v51, v51, v31
	v_mul_f32_e32 v52, v52, v32
	v_mul_f32_e32 v53, v53, v32
	v_mul_f32_e32 v54, v54, v32
	v_mul_f32_e32 v55, v55, v32
	v_mul_f32_e32 v56, v56, v33
	v_mul_f32_e32 v57, v57, v33
	v_mul_f32_e32 v58, v58, v33
	v_mul_f32_e32 v59, v59, v33
	v_mul_f32_e32 v60, v60, v34
	v_mul_f32_e32 v61, v61, v34
	v_mul_f32_e32 v62, v62, v34
	v_mul_f32_e32 v63, v63, v34
	v_mul_f32_e32 v64, v64, v35
	v_mul_f32_e32 v65, v65, v35
	v_mul_f32_e32 v66, v66, v35
	v_mul_f32_e32 v67, v67, v35

.Lp0_segok_l2:
	s_sub_u32 s26, s25, s7
	s_mul_hi_u32 s27, s26, s20
	s_mul_i32 s28, s27, s19
	s_sub_u32 s28, s26, s28
	s_lshl_b32 s29, s28, 5
	s_lshl_b32 s30, s27, 6
	s_mul_i32 s31, s30, s18
	s_lshl_b32 s34, s29, 2
	s_add_u32 s31, s31, s34
	s_add_u32 s56, s14, s31
	s_addc_u32 s57, s15, 0
	s_add_u32 s58, s56, s18
	s_addc_u32 s59, s57, 0
	s_add_u32 s60, s58, s18
	s_addc_u32 s61, s59, 0
	s_add_u32 s62, s60, s18
	s_addc_u32 s63, s61, 0
	s_add_u32 s64, s62, s18
	s_addc_u32 s65, s63, 0
	s_add_u32 s66, s64, s18
	s_addc_u32 s67, s65, 0
	s_add_u32 s68, s66, s18
	s_addc_u32 s69, s67, 0
	s_add_u32 s70, s68, s18
	s_addc_u32 s71, s69, 0
	s_lshl_b32 s34, s30, 2
	s_add_u32 s72, s16, s34
	s_addc_u32 s73, s17, 0
	s_cmpk_ge_u32 s29, 0x1600
	s_cselect_b32 s34, 1, 0
	s_and_b32 s34, s34, s24
	s_mul_i32 s35, s34, 0x1600
	s_sub_u32 s35, s29, s35
	s_lshr_b32 s36, s35, 7
	s_lshl_b32 s36, s36, 8
	s_lshl_b32 s37, s34, 7
	s_add_u32 s36, s36, s37
	s_and_b32 s37, s35, 0x7f
	s_add_u32 s36, s36, s37
	s_cmp_eq_u32 s24, 0
	s_cselect_b32 s36, s29, s36
	s_lshr_b32 s37, s36, 8
	s_mul_i32 s37, s37, s21
	s_add_u32 s37, s37, s27
	s_lshl_b32 s37, s37, 8
	s_and_b32 s38, s36, 0xff
	s_add_u32 s37, s37, s38
	s_lshl_b32 s37, s37, 7
	s_add_u32 s46, s22, s37
	s_addc_u32 s47, s23, 0
	s_mov_b32 s48, s13
	v_mad_u32_u24 v10, v2, s18, v1
	global_load_dwordx4 v[28:31], v3, s[72:73]
	global_load_dwordx4 v[32:35], v3, s[72:73] offset:16
	global_load_dwordx4 v[36:39], v10, s[56:57] nt
	global_load_dwordx4 v[40:43], v10, s[58:59] nt
	global_load_dwordx4 v[44:47], v10, s[60:61] nt
	global_load_dwordx4 v[48:51], v10, s[62:63] nt
	global_load_dwordx4 v[52:55], v10, s[64:65] nt
	global_load_dwordx4 v[56:59], v10, s[66:67] nt
	global_load_dwordx4 v[60:63], v10, s[68:69] nt
	global_load_dwordx4 v[64:67], v10, s[70:71] nt
	s_cmp_eq_u32 s76, 0
	s_cbranch_scc1 .Lp0_procb
	s_mov_b32 s76, 0
	s_waitcnt vmcnt(0)
	s_branch .Lp0_next
